# grid barrier: every workgroup invalidates its L1 at arrival (overlapped with the wait), the XCD's last arriver invalidates right after its L2 write-back; no invalidate after the release is observed
# speedup vs baseline: 1.0226x; 1.0226x over previous
; DI unsigned xb_ld(unsigned* p) { return __hip_atomic_load(p, __ATOMIC_RELAXED, __HIP_MEMORY_SCOPE_AGENT); }
; DI unsigned xb_add(unsigned* p, unsigned v) { return __hip_atomic_fetch_add(p, v, __ATOMIC_RELAXED, __HIP_MEMORY_SCOPE_AGENT); }
; #define XB_SPIN(cond, bar) do { unsigned _sp = 0; while (cond) { __builtin_amdgcn_s_sleep(1); \
;     if ((++_sp & 255u) == 0u) { if (xb_ld(&(bar)[XB_TMO])) break; if (_sp > XB_SPIN_CAP) { atomicAdd(&(bar)[XB_TMO], 1u); break; } } } } while (0)
; DI void xcd_barrier(const XcdBarrier& b) {
;     ...
;     const unsigned old = xb_add(&bar[XB_XSUB(b.x)], 1u);
;     const unsigned gen = old / nloc;
;     if (old + 1u == (gen + 1u) * nloc) {
;       __builtin_amdgcn_fence(__ATOMIC_RELEASE, "agent");
;       asm volatile("s_waitcnt vmcnt(0)" ::: "memory");
;       const unsigned og = xb_add(&bar[XB_TOP], 1u);
;       const unsigned tg = og / nx;
;       if (og + 1u == (tg + 1u) * nx) xb_add(&bar[XB_TOPGEN], 1u);
;       else XB_SPIN(xb_ld(&bar[XB_TOPGEN]) == tg, bar);
;       __builtin_amdgcn_fence(__ATOMIC_ACQUIRE, "agent");
;       xb_add(&bar[XB_XGEN(b.x)], 1u);
;       asm volatile("s_waitcnt vmcnt(0)" ::: "memory");
;     } else {
;       XB_SPIN(xb_ld(&bar[XB_XGEN(b.x)]) == gen, bar);
.LBB0_184:
	s_or_b64 exec, exec, s[14:15]
	v_cvt_f32_u32_e32 v4, v2
	s_waitcnt vmcnt(0)
	v_readfirstlane_b32 s0, v3
	buffer_inv sc1
	v_sub_u32_e32 v3, 0, v2
	v_rcp_iflag_f32_e32 v4, v4
	v_add_u32_e32 v5, s0, v1
	v_mul_f32_e32 v4, 0x4f7ffffe, v4
	v_cvt_u32_f32_e32 v4, v4
	v_mul_lo_u32 v1, v3, v4
	v_mul_hi_u32 v1, v4, v1
	v_add_u32_e32 v1, v4, v1
	v_mul_hi_u32 v1, v5, v1
	v_mul_lo_u32 v3, v1, v2
	v_sub_u32_e32 v3, v5, v3
	v_add_u32_e32 v4, 1, v1
	v_cmp_ge_u32_e32 vcc, v3, v2
	s_nop 1
	v_cndmask_b32_e32 v1, v1, v4, vcc
	v_sub_u32_e32 v4, v3, v2
	v_cndmask_b32_e32 v3, v3, v4, vcc
	v_add_u32_e32 v4, 1, v1
	v_cmp_ge_u32_e32 vcc, v3, v2
	v_add_u32_e32 v3, 1, v5
	s_nop 0
	v_cndmask_b32_e32 v1, v1, v4, vcc
	v_mul_lo_u32 v4, v2, v1
	v_add_u32_e32 v2, v4, v2
	v_cmp_ne_u32_e32 vcc, v3, v2
	s_and_saveexec_b64 s[0:1], vcc
	s_xor_b64 s[12:13], exec, s[0:1]
	s_cbranch_execz .LBB0_198
	s_waitcnt lgkmcnt(0)
	v_mov_b32_e32 v0, 0x2000
	global_load_dword v0, v0, s[10:11] offset:1024 sc1
	s_add_u32 s20, s10, 0x2400
	s_addc_u32 s21, s11, 0
	s_waitcnt vmcnt(0)
	v_cmp_eq_u32_e32 vcc, v0, v1
	s_and_saveexec_b64 s[14:15], vcc
	s_cbranch_execz .LBB0_197
	s_add_u32 s16, s86, 0xe7c1200
	s_addc_u32 s17, s87, 0
	s_mov_b32 s0, 1
	s_mov_b64 s[30:31], 0
	v_mov_b32_e32 v0, 0
	s_branch .LBB0_188

; DI unsigned xb_ld(unsigned* p) { return __hip_atomic_load(p, __ATOMIC_RELAXED, __HIP_MEMORY_SCOPE_AGENT); }
; DI unsigned xb_add(unsigned* p, unsigned v) { return __hip_atomic_fetch_add(p, v, __ATOMIC_RELAXED, __HIP_MEMORY_SCOPE_AGENT); }
; #define XB_SPIN(cond, bar) do { unsigned _sp = 0; while (cond) { __builtin_amdgcn_s_sleep(1); \
;     if ((++_sp & 255u) == 0u) { if (xb_ld(&(bar)[XB_TMO])) break; if (_sp > XB_SPIN_CAP) { atomicAdd(&(bar)[XB_TMO], 1u); break; } } } } while (0)
; DI void xcd_barrier(const XcdBarrier& b) {
;     ...
;     if (old + 1u == (gen + 1u) * nloc) {
;       __builtin_amdgcn_fence(__ATOMIC_RELEASE, "agent");
;       asm volatile("s_waitcnt vmcnt(0)" ::: "memory");
;       const unsigned og = xb_add(&bar[XB_TOP], 1u);
;       const unsigned tg = og / nx;
;       if (og + 1u == (tg + 1u) * nx) xb_add(&bar[XB_TOPGEN], 1u);
;       else XB_SPIN(xb_ld(&bar[XB_TOPGEN]) == tg, bar);
;       __builtin_amdgcn_fence(__ATOMIC_ACQUIRE, "agent");
;       xb_add(&bar[XB_XGEN(b.x)], 1u);
;       asm volatile("s_waitcnt vmcnt(0)" ::: "memory");
;     } else {
;       XB_SPIN(xb_ld(&bar[XB_XGEN(b.x)]) == gen, bar);
;       __builtin_amdgcn_fence(__ATOMIC_ACQUIRE, "agent");
;       asm volatile("s_waitcnt vmcnt(0)" ::: "memory");
.LBB0_197:
	s_or_b64 exec, exec, s[14:15]
	s_waitcnt vmcnt(0)
	s_waitcnt vmcnt(0)
.LBB0_198:
	s_andn2_saveexec_b64 s[0:1], s[12:13]
	s_cbranch_execz .LBB0_218
	s_mov_b64 s[12:13], exec
	buffer_wbl2 sc1
	s_waitcnt lgkmcnt(0)
	s_waitcnt vmcnt(0)
	buffer_inv sc1
	v_mbcnt_lo_u32_b32 v1, s12, 0
	v_mbcnt_hi_u32_b32 v1, s13, v1
	v_cmp_eq_u32_e32 vcc, 0, v1
	s_and_saveexec_b64 s[14:15], vcc
	s_cbranch_execz .LBB0_201
	s_bcnt1_i32_b64 s0, s[12:13]
	v_mov_b32_e32 v2, 0xe7c4000
	v_mov_b32_e32 v3, s0
	global_atomic_add v2, v2, v3, s[86:87] offset:1024 sc0

; DI unsigned xb_ld(unsigned* p) { return __hip_atomic_load(p, __ATOMIC_RELAXED, __HIP_MEMORY_SCOPE_AGENT); }
; DI unsigned xb_add(unsigned* p, unsigned v) { return __hip_atomic_fetch_add(p, v, __ATOMIC_RELAXED, __HIP_MEMORY_SCOPE_AGENT); }
; #define XB_SPIN(cond, bar) do { unsigned _sp = 0; while (cond) { __builtin_amdgcn_s_sleep(1); \
;     if ((++_sp & 255u) == 0u) { if (xb_ld(&(bar)[XB_TMO])) break; if (_sp > XB_SPIN_CAP) { atomicAdd(&(bar)[XB_TMO], 1u); break; } } } } while (0)
; DI void xcd_barrier(const XcdBarrier& b) {
;     ...
;       else XB_SPIN(xb_ld(&bar[XB_TOPGEN]) == tg, bar);
;       __builtin_amdgcn_fence(__ATOMIC_ACQUIRE, "agent");
;       xb_add(&bar[XB_XGEN(b.x)], 1u);
.LBB0_215:
	s_or_b64 exec, exec, s[12:13]
	s_mov_b64 s[12:13], exec
	v_mbcnt_lo_u32_b32 v0, s12, 0
	v_mbcnt_hi_u32_b32 v0, s13, v0
	v_cmp_eq_u32_e32 vcc, 0, v0
	s_waitcnt vmcnt(0)
	s_and_saveexec_b64 s[14:15], vcc
	s_cbranch_execz .LBB0_217
	s_bcnt1_i32_b64 s0, s[12:13]
	v_mov_b32_e32 v0, 0x2000
	v_mov_b32_e32 v1, s0
	global_atomic_add v0, v1, s[10:11] offset:1024

; DI unsigned xb_ld(unsigned* p) { return __hip_atomic_load(p, __ATOMIC_RELAXED, __HIP_MEMORY_SCOPE_AGENT); }
; DI unsigned xb_add(unsigned* p, unsigned v) { return __hip_atomic_fetch_add(p, v, __ATOMIC_RELAXED, __HIP_MEMORY_SCOPE_AGENT); }
; #define XB_SPIN(cond, bar) do { unsigned _sp = 0; while (cond) { __builtin_amdgcn_s_sleep(1); \
;     if ((++_sp & 255u) == 0u) { if (xb_ld(&(bar)[XB_TMO])) break; if (_sp > XB_SPIN_CAP) { atomicAdd(&(bar)[XB_TMO], 1u); break; } } } } while (0)
; DI void xcd_barrier(const XcdBarrier& b) {
;     ...
;     const unsigned old = xb_add(&bar[XB_XSUB(b.x)], 1u);
;     const unsigned gen = old / nloc;
;     if (old + 1u == (gen + 1u) * nloc) {
;       __builtin_amdgcn_fence(__ATOMIC_RELEASE, "agent");
;       asm volatile("s_waitcnt vmcnt(0)" ::: "memory");
;       const unsigned og = xb_add(&bar[XB_TOP], 1u);
;       const unsigned tg = og / nx;
;       if (og + 1u == (tg + 1u) * nx) xb_add(&bar[XB_TOPGEN], 1u);
;       else XB_SPIN(xb_ld(&bar[XB_TOPGEN]) == tg, bar);
;       __builtin_amdgcn_fence(__ATOMIC_ACQUIRE, "agent");
;       xb_add(&bar[XB_XGEN(b.x)], 1u);
;       asm volatile("s_waitcnt vmcnt(0)" ::: "memory");
;     } else {
;       XB_SPIN(xb_ld(&bar[XB_XGEN(b.x)]) == gen, bar);
.LBB0_249:
	s_or_b64 exec, exec, s[12:13]
	v_cvt_f32_u32_e32 v4, v2
	s_waitcnt vmcnt(0)
	v_readfirstlane_b32 s0, v3
	buffer_inv sc1
	v_sub_u32_e32 v3, 0, v2
	v_rcp_iflag_f32_e32 v4, v4
	v_add_u32_e32 v5, s0, v1
	v_mul_f32_e32 v4, 0x4f7ffffe, v4
	v_cvt_u32_f32_e32 v4, v4
	v_mul_lo_u32 v1, v3, v4
	v_mul_hi_u32 v1, v4, v1
	v_add_u32_e32 v1, v4, v1
	v_mul_hi_u32 v1, v5, v1
	v_mul_lo_u32 v3, v1, v2
	v_sub_u32_e32 v3, v5, v3
	v_add_u32_e32 v4, 1, v1
	v_cmp_ge_u32_e32 vcc, v3, v2
	s_nop 1
	v_cndmask_b32_e32 v1, v1, v4, vcc
	v_sub_u32_e32 v4, v3, v2
	v_cndmask_b32_e32 v3, v3, v4, vcc
	v_add_u32_e32 v4, 1, v1
	v_cmp_ge_u32_e32 vcc, v3, v2
	v_add_u32_e32 v3, 1, v5
	s_nop 0
	v_cndmask_b32_e32 v1, v1, v4, vcc
	v_mul_lo_u32 v4, v2, v1
	v_add_u32_e32 v2, v4, v2
	v_cmp_ne_u32_e32 vcc, v3, v2
	s_and_saveexec_b64 s[0:1], vcc
	s_xor_b64 s[10:11], exec, s[0:1]
	s_cbranch_execz .LBB0_263
	s_waitcnt lgkmcnt(0)
	v_mov_b32_e32 v0, 0x2000
	global_load_dword v0, v0, s[8:9] offset:1024 sc1
	s_add_u32 s16, s8, 0x2400
	s_addc_u32 s17, s9, 0
	s_waitcnt vmcnt(0)
	v_cmp_eq_u32_e32 vcc, v0, v1
	s_and_saveexec_b64 s[12:13], vcc
	s_cbranch_execz .LBB0_262
	s_add_u32 s14, s86, 0xe7c1200
	s_addc_u32 s15, s87, 0
	s_mov_b32 s0, 1
	s_mov_b64 s[20:21], 0
	v_mov_b32_e32 v0, 0
	s_branch .LBB0_253

; DI unsigned xb_ld(unsigned* p) { return __hip_atomic_load(p, __ATOMIC_RELAXED, __HIP_MEMORY_SCOPE_AGENT); }
; DI unsigned xb_add(unsigned* p, unsigned v) { return __hip_atomic_fetch_add(p, v, __ATOMIC_RELAXED, __HIP_MEMORY_SCOPE_AGENT); }
; #define XB_SPIN(cond, bar) do { unsigned _sp = 0; while (cond) { __builtin_amdgcn_s_sleep(1); \
;     if ((++_sp & 255u) == 0u) { if (xb_ld(&(bar)[XB_TMO])) break; if (_sp > XB_SPIN_CAP) { atomicAdd(&(bar)[XB_TMO], 1u); break; } } } } while (0)
; DI void xcd_barrier(const XcdBarrier& b) {
;     ...
;     if (old + 1u == (gen + 1u) * nloc) {
;       __builtin_amdgcn_fence(__ATOMIC_RELEASE, "agent");
;       asm volatile("s_waitcnt vmcnt(0)" ::: "memory");
;       const unsigned og = xb_add(&bar[XB_TOP], 1u);
;       const unsigned tg = og / nx;
;       if (og + 1u == (tg + 1u) * nx) xb_add(&bar[XB_TOPGEN], 1u);
;       else XB_SPIN(xb_ld(&bar[XB_TOPGEN]) == tg, bar);
;       __builtin_amdgcn_fence(__ATOMIC_ACQUIRE, "agent");
;       xb_add(&bar[XB_XGEN(b.x)], 1u);
;       asm volatile("s_waitcnt vmcnt(0)" ::: "memory");
;     } else {
;       XB_SPIN(xb_ld(&bar[XB_XGEN(b.x)]) == gen, bar);
;       __builtin_amdgcn_fence(__ATOMIC_ACQUIRE, "agent");
;       asm volatile("s_waitcnt vmcnt(0)" ::: "memory");
.LBB0_262:
	s_or_b64 exec, exec, s[12:13]
	s_waitcnt vmcnt(0)
	s_waitcnt vmcnt(0)
.LBB0_263:
	s_andn2_saveexec_b64 s[0:1], s[10:11]
	s_cbranch_execz .LBB0_283
	s_mov_b64 s[10:11], exec
	buffer_wbl2 sc1
	s_waitcnt lgkmcnt(0)
	s_waitcnt vmcnt(0)
	buffer_inv sc1
	v_mbcnt_lo_u32_b32 v1, s10, 0
	v_mbcnt_hi_u32_b32 v1, s11, v1
	v_cmp_eq_u32_e32 vcc, 0, v1
	s_and_saveexec_b64 s[12:13], vcc
	s_cbranch_execz .LBB0_266
	s_bcnt1_i32_b64 s0, s[10:11]
	v_mov_b32_e32 v2, 0xe7c4000
	v_mov_b32_e32 v3, s0
	global_atomic_add v2, v2, v3, s[86:87] offset:1024 sc0

; DI unsigned xb_ld(unsigned* p) { return __hip_atomic_load(p, __ATOMIC_RELAXED, __HIP_MEMORY_SCOPE_AGENT); }
; DI unsigned xb_add(unsigned* p, unsigned v) { return __hip_atomic_fetch_add(p, v, __ATOMIC_RELAXED, __HIP_MEMORY_SCOPE_AGENT); }
; #define XB_SPIN(cond, bar) do { unsigned _sp = 0; while (cond) { __builtin_amdgcn_s_sleep(1); \
;     if ((++_sp & 255u) == 0u) { if (xb_ld(&(bar)[XB_TMO])) break; if (_sp > XB_SPIN_CAP) { atomicAdd(&(bar)[XB_TMO], 1u); break; } } } } while (0)
; DI void xcd_barrier(const XcdBarrier& b) {
;     ...
;       else XB_SPIN(xb_ld(&bar[XB_TOPGEN]) == tg, bar);
;       __builtin_amdgcn_fence(__ATOMIC_ACQUIRE, "agent");
;       xb_add(&bar[XB_XGEN(b.x)], 1u);
.LBB0_280:
	s_or_b64 exec, exec, s[10:11]
	s_mov_b64 s[10:11], exec
	v_mbcnt_lo_u32_b32 v0, s10, 0
	v_mbcnt_hi_u32_b32 v0, s11, v0
	v_cmp_eq_u32_e32 vcc, 0, v0
	s_waitcnt vmcnt(0)
	s_and_saveexec_b64 s[12:13], vcc
	s_cbranch_execz .LBB0_282
	s_bcnt1_i32_b64 s0, s[10:11]
	v_mov_b32_e32 v0, 0x2000
	v_mov_b32_e32 v1, s0
	global_atomic_add v0, v1, s[8:9] offset:1024

; DI unsigned xb_ld(unsigned* p) { return __hip_atomic_load(p, __ATOMIC_RELAXED, __HIP_MEMORY_SCOPE_AGENT); }
; DI unsigned xb_add(unsigned* p, unsigned v) { return __hip_atomic_fetch_add(p, v, __ATOMIC_RELAXED, __HIP_MEMORY_SCOPE_AGENT); }
; #define XB_SPIN(cond, bar) do { unsigned _sp = 0; while (cond) { __builtin_amdgcn_s_sleep(1); \
;     if ((++_sp & 255u) == 0u) { if (xb_ld(&(bar)[XB_TMO])) break; if (_sp > XB_SPIN_CAP) { atomicAdd(&(bar)[XB_TMO], 1u); break; } } } } while (0)
; DI void xcd_barrier(const XcdBarrier& b) {
;     ...
;     const unsigned old = xb_add(&bar[XB_XSUB(b.x)], 1u);
;     const unsigned gen = old / nloc;
;     if (old + 1u == (gen + 1u) * nloc) {
;       __builtin_amdgcn_fence(__ATOMIC_RELEASE, "agent");
;       asm volatile("s_waitcnt vmcnt(0)" ::: "memory");
;       const unsigned og = xb_add(&bar[XB_TOP], 1u);
;       const unsigned tg = og / nx;
;       if (og + 1u == (tg + 1u) * nx) xb_add(&bar[XB_TOPGEN], 1u);
;       else XB_SPIN(xb_ld(&bar[XB_TOPGEN]) == tg, bar);
;       __builtin_amdgcn_fence(__ATOMIC_ACQUIRE, "agent");
;       xb_add(&bar[XB_XGEN(b.x)], 1u);
;       asm volatile("s_waitcnt vmcnt(0)" ::: "memory");
;     } else {
;       XB_SPIN(xb_ld(&bar[XB_XGEN(b.x)]) == gen, bar);
.LBB0_490:
	s_or_b64 exec, exec, s[12:13]
	v_cvt_f32_u32_e32 v4, v2
	s_waitcnt vmcnt(0)
	v_readfirstlane_b32 s0, v3
	buffer_inv sc1
	v_sub_u32_e32 v3, 0, v2
	v_rcp_iflag_f32_e32 v4, v4
	v_add_u32_e32 v5, s0, v1
	v_mul_f32_e32 v4, 0x4f7ffffe, v4
	v_cvt_u32_f32_e32 v4, v4
	v_mul_lo_u32 v1, v3, v4
	v_mul_hi_u32 v1, v4, v1
	v_add_u32_e32 v1, v4, v1
	v_mul_hi_u32 v1, v5, v1
	v_mul_lo_u32 v3, v1, v2
	v_sub_u32_e32 v3, v5, v3
	v_add_u32_e32 v4, 1, v1
	v_cmp_ge_u32_e32 vcc, v3, v2
	s_nop 1
	v_cndmask_b32_e32 v1, v1, v4, vcc
	v_sub_u32_e32 v4, v3, v2
	v_cndmask_b32_e32 v3, v3, v4, vcc
	v_add_u32_e32 v4, 1, v1
	v_cmp_ge_u32_e32 vcc, v3, v2
	v_add_u32_e32 v3, 1, v5
	s_nop 0
	v_cndmask_b32_e32 v1, v1, v4, vcc
	v_mul_lo_u32 v4, v2, v1
	v_add_u32_e32 v2, v4, v2
	v_cmp_ne_u32_e32 vcc, v3, v2
	s_and_saveexec_b64 s[0:1], vcc
	s_xor_b64 s[10:11], exec, s[0:1]
	s_cbranch_execz .LBB0_504
	s_waitcnt lgkmcnt(0)
	v_mov_b32_e32 v0, 0x2000
	global_load_dword v0, v0, s[8:9] offset:1024 sc1
	s_add_u32 s16, s8, 0x2400
	s_addc_u32 s17, s9, 0
	s_waitcnt vmcnt(0)
	v_cmp_eq_u32_e32 vcc, v0, v1
	s_and_saveexec_b64 s[12:13], vcc
	s_cbranch_execz .LBB0_503
	s_add_u32 s14, s86, 0xe7c1200
	s_addc_u32 s15, s87, 0
	s_mov_b32 s0, 1
	s_mov_b64 s[30:31], 0
	v_mov_b32_e32 v0, 0
	s_branch .LBB0_494

; DI unsigned xb_ld(unsigned* p) { return __hip_atomic_load(p, __ATOMIC_RELAXED, __HIP_MEMORY_SCOPE_AGENT); }
; DI unsigned xb_add(unsigned* p, unsigned v) { return __hip_atomic_fetch_add(p, v, __ATOMIC_RELAXED, __HIP_MEMORY_SCOPE_AGENT); }
; #define XB_SPIN(cond, bar) do { unsigned _sp = 0; while (cond) { __builtin_amdgcn_s_sleep(1); \
;     if ((++_sp & 255u) == 0u) { if (xb_ld(&(bar)[XB_TMO])) break; if (_sp > XB_SPIN_CAP) { atomicAdd(&(bar)[XB_TMO], 1u); break; } } } } while (0)
; DI void xcd_barrier(const XcdBarrier& b) {
;     ...
;     const unsigned old = xb_add(&bar[XB_XSUB(b.x)], 1u);
;     const unsigned gen = old / nloc;
;     if (old + 1u == (gen + 1u) * nloc) {
;       __builtin_amdgcn_fence(__ATOMIC_RELEASE, "agent");
;       asm volatile("s_waitcnt vmcnt(0)" ::: "memory");
;       const unsigned og = xb_add(&bar[XB_TOP], 1u);
;       const unsigned tg = og / nx;
;       if (og + 1u == (tg + 1u) * nx) xb_add(&bar[XB_TOPGEN], 1u);
;       else XB_SPIN(xb_ld(&bar[XB_TOPGEN]) == tg, bar);
;       __builtin_amdgcn_fence(__ATOMIC_ACQUIRE, "agent");
;       xb_add(&bar[XB_XGEN(b.x)], 1u);
;       asm volatile("s_waitcnt vmcnt(0)" ::: "memory");
;     } else {
;       XB_SPIN(xb_ld(&bar[XB_XGEN(b.x)]) == gen, bar);
.LBB0_829:
	s_or_b64 exec, exec, s[12:13]
	v_cvt_f32_u32_e32 v4, v2
	s_waitcnt vmcnt(0)
	v_readfirstlane_b32 s0, v3
	buffer_inv sc1
	v_sub_u32_e32 v3, 0, v2
	v_rcp_iflag_f32_e32 v4, v4
	v_add_u32_e32 v5, s0, v1
	v_mul_f32_e32 v4, 0x4f7ffffe, v4
	v_cvt_u32_f32_e32 v4, v4
	v_mul_lo_u32 v1, v3, v4
	v_mul_hi_u32 v1, v4, v1
	v_add_u32_e32 v1, v4, v1
	v_mul_hi_u32 v1, v5, v1
	v_mul_lo_u32 v3, v1, v2
	v_sub_u32_e32 v3, v5, v3
	v_add_u32_e32 v4, 1, v1
	v_cmp_ge_u32_e32 vcc, v3, v2
	s_nop 1
	v_cndmask_b32_e32 v1, v1, v4, vcc
	v_sub_u32_e32 v4, v3, v2
	v_cndmask_b32_e32 v3, v3, v4, vcc
	v_add_u32_e32 v4, 1, v1
	v_cmp_ge_u32_e32 vcc, v3, v2
	v_add_u32_e32 v3, 1, v5
	s_nop 0
	v_cndmask_b32_e32 v1, v1, v4, vcc
	v_mul_lo_u32 v4, v2, v1
	v_add_u32_e32 v2, v4, v2
	v_cmp_ne_u32_e32 vcc, v3, v2
	s_and_saveexec_b64 s[0:1], vcc
	s_xor_b64 s[10:11], exec, s[0:1]
	s_cbranch_execz .LBB0_843
	s_waitcnt lgkmcnt(0)
	v_mov_b32_e32 v0, 0x2000
	global_load_dword v0, v0, s[8:9] offset:1024 sc1
	s_add_u32 s16, s8, 0x2400
	s_addc_u32 s17, s9, 0
	s_waitcnt vmcnt(0)
	v_cmp_eq_u32_e32 vcc, v0, v1
	s_and_saveexec_b64 s[12:13], vcc
	s_cbranch_execz .LBB0_842
	s_add_u32 s14, s86, 0xe7c1200
	s_addc_u32 s15, s87, 0
	s_mov_b32 s0, 1
	s_mov_b64 s[26:27], 0
	v_mov_b32_e32 v0, 0
	s_branch .LBB0_833

; DI unsigned xb_ld(unsigned* p) { return __hip_atomic_load(p, __ATOMIC_RELAXED, __HIP_MEMORY_SCOPE_AGENT); }
; DI unsigned xb_add(unsigned* p, unsigned v) { return __hip_atomic_fetch_add(p, v, __ATOMIC_RELAXED, __HIP_MEMORY_SCOPE_AGENT); }
; #define XB_SPIN(cond, bar) do { unsigned _sp = 0; while (cond) { __builtin_amdgcn_s_sleep(1); \
;     if ((++_sp & 255u) == 0u) { if (xb_ld(&(bar)[XB_TMO])) break; if (_sp > XB_SPIN_CAP) { atomicAdd(&(bar)[XB_TMO], 1u); break; } } } } while (0)
; DI void xcd_barrier(const XcdBarrier& b) {
;     ...
;     const unsigned old = xb_add(&bar[XB_XSUB(b.x)], 1u);
;     const unsigned gen = old / nloc;
;     if (old + 1u == (gen + 1u) * nloc) {
;       __builtin_amdgcn_fence(__ATOMIC_RELEASE, "agent");
;       asm volatile("s_waitcnt vmcnt(0)" ::: "memory");
;       const unsigned og = xb_add(&bar[XB_TOP], 1u);
;       const unsigned tg = og / nx;
;       if (og + 1u == (tg + 1u) * nx) xb_add(&bar[XB_TOPGEN], 1u);
;       else XB_SPIN(xb_ld(&bar[XB_TOPGEN]) == tg, bar);
;       __builtin_amdgcn_fence(__ATOMIC_ACQUIRE, "agent");
;       xb_add(&bar[XB_XGEN(b.x)], 1u);
;       asm volatile("s_waitcnt vmcnt(0)" ::: "memory");
;     } else {
;       XB_SPIN(xb_ld(&bar[XB_XGEN(b.x)]) == gen, bar);
.LBB0_941:
	s_or_b64 exec, exec, s[12:13]
	v_cvt_f32_u32_e32 v4, v2
	s_waitcnt vmcnt(0)
	v_readfirstlane_b32 s0, v3
	buffer_inv sc1
	v_sub_u32_e32 v3, 0, v2
	v_rcp_iflag_f32_e32 v4, v4
	v_add_u32_e32 v5, s0, v1
	v_mul_f32_e32 v4, 0x4f7ffffe, v4
	v_cvt_u32_f32_e32 v4, v4
	v_mul_lo_u32 v1, v3, v4
	v_mul_hi_u32 v1, v4, v1
	v_add_u32_e32 v1, v4, v1
	v_mul_hi_u32 v1, v5, v1
	v_mul_lo_u32 v3, v1, v2
	v_sub_u32_e32 v3, v5, v3
	v_add_u32_e32 v4, 1, v1
	v_cmp_ge_u32_e32 vcc, v3, v2
	s_nop 1
	v_cndmask_b32_e32 v1, v1, v4, vcc
	v_sub_u32_e32 v4, v3, v2
	v_cndmask_b32_e32 v3, v3, v4, vcc
	v_add_u32_e32 v4, 1, v1
	v_cmp_ge_u32_e32 vcc, v3, v2
	v_add_u32_e32 v3, 1, v5
	s_nop 0
	v_cndmask_b32_e32 v1, v1, v4, vcc
	v_mul_lo_u32 v4, v2, v1
	v_add_u32_e32 v2, v4, v2
	v_cmp_ne_u32_e32 vcc, v3, v2
	s_and_saveexec_b64 s[0:1], vcc
	s_xor_b64 s[10:11], exec, s[0:1]
	s_cbranch_execz .LBB0_955
	s_waitcnt lgkmcnt(0)
	v_mov_b32_e32 v0, 0x2000
	global_load_dword v0, v0, s[8:9] offset:1024 sc1
	s_add_u32 s16, s8, 0x2400
	s_addc_u32 s17, s9, 0
	s_waitcnt vmcnt(0)
	v_cmp_eq_u32_e32 vcc, v0, v1
	s_and_saveexec_b64 s[12:13], vcc
	s_cbranch_execz .LBB0_954
	s_add_u32 s14, s86, 0xe7c1200
	s_addc_u32 s15, s87, 0
	s_mov_b32 s0, 1
	s_mov_b64 s[24:25], 0
	v_mov_b32_e32 v0, 0
	s_branch .LBB0_945

; DI unsigned xb_ld(unsigned* p) { return __hip_atomic_load(p, __ATOMIC_RELAXED, __HIP_MEMORY_SCOPE_AGENT); }
; DI unsigned xb_add(unsigned* p, unsigned v) { return __hip_atomic_fetch_add(p, v, __ATOMIC_RELAXED, __HIP_MEMORY_SCOPE_AGENT); }
; #define XB_SPIN(cond, bar) do { unsigned _sp = 0; while (cond) { __builtin_amdgcn_s_sleep(1); \
;     if ((++_sp & 255u) == 0u) { if (xb_ld(&(bar)[XB_TMO])) break; if (_sp > XB_SPIN_CAP) { atomicAdd(&(bar)[XB_TMO], 1u); break; } } } } while (0)
; DI void xcd_barrier(const XcdBarrier& b) {
;     ...
;     const unsigned old = xb_add(&bar[XB_XSUB(b.x)], 1u);
;     const unsigned gen = old / nloc;
;     if (old + 1u == (gen + 1u) * nloc) {
;       __builtin_amdgcn_fence(__ATOMIC_RELEASE, "agent");
;       asm volatile("s_waitcnt vmcnt(0)" ::: "memory");
;       const unsigned og = xb_add(&bar[XB_TOP], 1u);
;       const unsigned tg = og / nx;
;       if (og + 1u == (tg + 1u) * nx) xb_add(&bar[XB_TOPGEN], 1u);
;       else XB_SPIN(xb_ld(&bar[XB_TOPGEN]) == tg, bar);
;       __builtin_amdgcn_fence(__ATOMIC_ACQUIRE, "agent");
;       xb_add(&bar[XB_XGEN(b.x)], 1u);
;       asm volatile("s_waitcnt vmcnt(0)" ::: "memory");
;     } else {
;       XB_SPIN(xb_ld(&bar[XB_XGEN(b.x)]) == gen, bar);
.LBB0_1067:
	s_or_b64 exec, exec, s[22:23]
	v_cvt_f32_u32_e32 v4, v2
	s_waitcnt vmcnt(0)
	v_readfirstlane_b32 s0, v3
	buffer_inv sc1
	v_sub_u32_e32 v3, 0, v2
	v_rcp_iflag_f32_e32 v4, v4
	v_add_u32_e32 v5, s0, v1
	v_mul_f32_e32 v4, 0x4f7ffffe, v4
	v_cvt_u32_f32_e32 v4, v4
	v_mul_lo_u32 v1, v3, v4
	v_mul_hi_u32 v1, v4, v1
	v_add_u32_e32 v1, v4, v1
	v_mul_hi_u32 v1, v5, v1
	v_mul_lo_u32 v3, v1, v2
	v_sub_u32_e32 v3, v5, v3
	v_add_u32_e32 v4, 1, v1
	v_cmp_ge_u32_e32 vcc, v3, v2
	s_nop 1
	v_cndmask_b32_e32 v1, v1, v4, vcc
	v_sub_u32_e32 v4, v3, v2
	v_cndmask_b32_e32 v3, v3, v4, vcc
	v_add_u32_e32 v4, 1, v1
	v_cmp_ge_u32_e32 vcc, v3, v2
	v_add_u32_e32 v3, 1, v5
	s_nop 0
	v_cndmask_b32_e32 v1, v1, v4, vcc
	v_mul_lo_u32 v4, v2, v1
	v_add_u32_e32 v2, v4, v2
	v_cmp_ne_u32_e32 vcc, v3, v2
	s_and_saveexec_b64 s[0:1], vcc
	s_xor_b64 s[16:17], exec, s[0:1]
	s_cbranch_execz .LBB0_1081
	s_waitcnt lgkmcnt(0)
	v_mov_b32_e32 v0, 0x2000
	global_load_dword v0, v0, s[14:15] offset:1024 sc1
	s_add_u32 s26, s14, 0x2400
	s_addc_u32 s27, s15, 0
	s_waitcnt vmcnt(0)
	v_cmp_eq_u32_e32 vcc, v0, v1
	s_and_saveexec_b64 s[22:23], vcc
	s_cbranch_execz .LBB0_1080
	s_add_u32 s24, s86, 0xe7c1200
	s_addc_u32 s25, s87, 0
	s_mov_b32 s0, 1
	s_mov_b64 s[28:29], 0
	v_mov_b32_e32 v0, 0
	s_branch .LBB0_1071

; DI unsigned xb_ld(unsigned* p) { return __hip_atomic_load(p, __ATOMIC_RELAXED, __HIP_MEMORY_SCOPE_AGENT); }
; DI unsigned xb_add(unsigned* p, unsigned v) { return __hip_atomic_fetch_add(p, v, __ATOMIC_RELAXED, __HIP_MEMORY_SCOPE_AGENT); }
; #define XB_SPIN(cond, bar) do { unsigned _sp = 0; while (cond) { __builtin_amdgcn_s_sleep(1); \
;     if ((++_sp & 255u) == 0u) { if (xb_ld(&(bar)[XB_TMO])) break; if (_sp > XB_SPIN_CAP) { atomicAdd(&(bar)[XB_TMO], 1u); break; } } } } while (0)
; DI void xcd_barrier(const XcdBarrier& b) {
;     ...
;     if (old + 1u == (gen + 1u) * nloc) {
;       __builtin_amdgcn_fence(__ATOMIC_RELEASE, "agent");
;       asm volatile("s_waitcnt vmcnt(0)" ::: "memory");
;       const unsigned og = xb_add(&bar[XB_TOP], 1u);
;       const unsigned tg = og / nx;
;       if (og + 1u == (tg + 1u) * nx) xb_add(&bar[XB_TOPGEN], 1u);
;       else XB_SPIN(xb_ld(&bar[XB_TOPGEN]) == tg, bar);
;       __builtin_amdgcn_fence(__ATOMIC_ACQUIRE, "agent");
;       xb_add(&bar[XB_XGEN(b.x)], 1u);
;       asm volatile("s_waitcnt vmcnt(0)" ::: "memory");
;     } else {
;       XB_SPIN(xb_ld(&bar[XB_XGEN(b.x)]) == gen, bar);
;       __builtin_amdgcn_fence(__ATOMIC_ACQUIRE, "agent");
;       asm volatile("s_waitcnt vmcnt(0)" ::: "memory");
.LBB0_1080:
	s_or_b64 exec, exec, s[22:23]
	s_waitcnt vmcnt(0)
	s_waitcnt vmcnt(0)
.LBB0_1081:
	s_andn2_saveexec_b64 s[0:1], s[16:17]
	s_cbranch_execz .LBB0_1101
	s_mov_b64 s[16:17], exec
	buffer_wbl2 sc1
	s_waitcnt lgkmcnt(0)
	s_waitcnt vmcnt(0)
	buffer_inv sc1
	v_mbcnt_lo_u32_b32 v1, s16, 0
	v_mbcnt_hi_u32_b32 v1, s17, v1
	v_cmp_eq_u32_e32 vcc, 0, v1
	s_and_saveexec_b64 s[22:23], vcc
	s_cbranch_execz .LBB0_1084
	s_bcnt1_i32_b64 s0, s[16:17]
	v_mov_b32_e32 v2, 0xe7c4000
	v_mov_b32_e32 v3, s0
	global_atomic_add v2, v2, v3, s[86:87] offset:1024 sc0

; DI unsigned xb_ld(unsigned* p) { return __hip_atomic_load(p, __ATOMIC_RELAXED, __HIP_MEMORY_SCOPE_AGENT); }
; DI unsigned xb_add(unsigned* p, unsigned v) { return __hip_atomic_fetch_add(p, v, __ATOMIC_RELAXED, __HIP_MEMORY_SCOPE_AGENT); }
; #define XB_SPIN(cond, bar) do { unsigned _sp = 0; while (cond) { __builtin_amdgcn_s_sleep(1); \
;     if ((++_sp & 255u) == 0u) { if (xb_ld(&(bar)[XB_TMO])) break; if (_sp > XB_SPIN_CAP) { atomicAdd(&(bar)[XB_TMO], 1u); break; } } } } while (0)
; DI void xcd_barrier(const XcdBarrier& b) {
;     ...
;       else XB_SPIN(xb_ld(&bar[XB_TOPGEN]) == tg, bar);
;       __builtin_amdgcn_fence(__ATOMIC_ACQUIRE, "agent");
;       xb_add(&bar[XB_XGEN(b.x)], 1u);
.LBB0_1098:
	s_or_b64 exec, exec, s[16:17]
	s_mov_b64 s[16:17], exec
	v_mbcnt_lo_u32_b32 v0, s16, 0
	v_mbcnt_hi_u32_b32 v0, s17, v0
	v_cmp_eq_u32_e32 vcc, 0, v0
	s_waitcnt vmcnt(0)
	s_and_saveexec_b64 s[22:23], vcc
	s_cbranch_execz .LBB0_1100
	s_bcnt1_i32_b64 s0, s[16:17]
	v_mov_b32_e32 v0, 0x2000
	v_mov_b32_e32 v1, s0
	global_atomic_add v0, v1, s[14:15] offset:1024

; DI unsigned xb_ld(unsigned* p) { return __hip_atomic_load(p, __ATOMIC_RELAXED, __HIP_MEMORY_SCOPE_AGENT); }
; DI unsigned xb_add(unsigned* p, unsigned v) { return __hip_atomic_fetch_add(p, v, __ATOMIC_RELAXED, __HIP_MEMORY_SCOPE_AGENT); }
; #define XB_SPIN(cond, bar) do { unsigned _sp = 0; while (cond) { __builtin_amdgcn_s_sleep(1); \
;     if ((++_sp & 255u) == 0u) { if (xb_ld(&(bar)[XB_TMO])) break; if (_sp > XB_SPIN_CAP) { atomicAdd(&(bar)[XB_TMO], 1u); break; } } } } while (0)
; DI void xcd_barrier(const XcdBarrier& b) {
;     ...
;     const unsigned old = xb_add(&bar[XB_XSUB(b.x)], 1u);
;     const unsigned gen = old / nloc;
;     if (old + 1u == (gen + 1u) * nloc) {
;       __builtin_amdgcn_fence(__ATOMIC_RELEASE, "agent");
;       asm volatile("s_waitcnt vmcnt(0)" ::: "memory");
;       const unsigned og = xb_add(&bar[XB_TOP], 1u);
;       const unsigned tg = og / nx;
;       if (og + 1u == (tg + 1u) * nx) xb_add(&bar[XB_TOPGEN], 1u);
;       else XB_SPIN(xb_ld(&bar[XB_TOPGEN]) == tg, bar);
;       __builtin_amdgcn_fence(__ATOMIC_ACQUIRE, "agent");
;       xb_add(&bar[XB_XGEN(b.x)], 1u);
;       asm volatile("s_waitcnt vmcnt(0)" ::: "memory");
;     } else {
;       XB_SPIN(xb_ld(&bar[XB_XGEN(b.x)]) == gen, bar);
.LBB0_1136:
	s_or_b64 exec, exec, s[12:13]
	v_cvt_f32_u32_e32 v4, v2
	s_waitcnt vmcnt(0)
	v_readfirstlane_b32 s0, v3
	buffer_inv sc1
	v_sub_u32_e32 v3, 0, v2
	v_rcp_iflag_f32_e32 v4, v4
	v_add_u32_e32 v5, s0, v1
	v_mul_f32_e32 v4, 0x4f7ffffe, v4
	v_cvt_u32_f32_e32 v4, v4
	v_mul_lo_u32 v1, v3, v4
	v_mul_hi_u32 v1, v4, v1
	v_add_u32_e32 v1, v4, v1
	v_mul_hi_u32 v1, v5, v1
	v_mul_lo_u32 v3, v1, v2
	v_sub_u32_e32 v3, v5, v3
	v_add_u32_e32 v4, 1, v1
	v_cmp_ge_u32_e32 vcc, v3, v2
	s_nop 1
	v_cndmask_b32_e32 v1, v1, v4, vcc
	v_sub_u32_e32 v4, v3, v2
	v_cndmask_b32_e32 v3, v3, v4, vcc
	v_add_u32_e32 v4, 1, v1
	v_cmp_ge_u32_e32 vcc, v3, v2
	v_add_u32_e32 v3, 1, v5
	s_nop 0
	v_cndmask_b32_e32 v1, v1, v4, vcc
	v_mul_lo_u32 v4, v2, v1
	v_add_u32_e32 v2, v4, v2
	v_cmp_ne_u32_e32 vcc, v3, v2
	s_and_saveexec_b64 s[0:1], vcc
	s_xor_b64 s[10:11], exec, s[0:1]
	s_cbranch_execz .LBB0_1150
	s_waitcnt lgkmcnt(0)
	v_mov_b32_e32 v0, 0x2000
	global_load_dword v0, v0, s[8:9] offset:1024 sc1
	s_add_u32 s16, s8, 0x2400
	s_addc_u32 s17, s9, 0
	s_waitcnt vmcnt(0)
	v_cmp_eq_u32_e32 vcc, v0, v1
	s_and_saveexec_b64 s[12:13], vcc
	s_cbranch_execz .LBB0_1149
	s_add_u32 s14, s86, 0xe7c1200
	s_addc_u32 s15, s87, 0
	s_mov_b32 s0, 1
	s_mov_b64 s[22:23], 0
	v_mov_b32_e32 v0, 0
	s_branch .LBB0_1140

; DI unsigned xb_ld(unsigned* p) { return __hip_atomic_load(p, __ATOMIC_RELAXED, __HIP_MEMORY_SCOPE_AGENT); }
; DI unsigned xb_add(unsigned* p, unsigned v) { return __hip_atomic_fetch_add(p, v, __ATOMIC_RELAXED, __HIP_MEMORY_SCOPE_AGENT); }
; #define XB_SPIN(cond, bar) do { unsigned _sp = 0; while (cond) { __builtin_amdgcn_s_sleep(1); \
;     if ((++_sp & 255u) == 0u) { if (xb_ld(&(bar)[XB_TMO])) break; if (_sp > XB_SPIN_CAP) { atomicAdd(&(bar)[XB_TMO], 1u); break; } } } } while (0)
; DI void xcd_barrier(const XcdBarrier& b) {
;     ...
;     const unsigned old = xb_add(&bar[XB_XSUB(b.x)], 1u);
;     const unsigned gen = old / nloc;
;     if (old + 1u == (gen + 1u) * nloc) {
;       __builtin_amdgcn_fence(__ATOMIC_RELEASE, "agent");
;       asm volatile("s_waitcnt vmcnt(0)" ::: "memory");
;       const unsigned og = xb_add(&bar[XB_TOP], 1u);
;       const unsigned tg = og / nx;
;       if (og + 1u == (tg + 1u) * nx) xb_add(&bar[XB_TOPGEN], 1u);
;       else XB_SPIN(xb_ld(&bar[XB_TOPGEN]) == tg, bar);
;       __builtin_amdgcn_fence(__ATOMIC_ACQUIRE, "agent");
;       xb_add(&bar[XB_XGEN(b.x)], 1u);
;       asm volatile("s_waitcnt vmcnt(0)" ::: "memory");
;     } else {
;       XB_SPIN(xb_ld(&bar[XB_XGEN(b.x)]) == gen, bar);
.LBB0_1193:
	s_or_b64 exec, exec, s[10:11]
	v_cvt_f32_u32_e32 v4, v2
	s_waitcnt vmcnt(0)
	v_readfirstlane_b32 s0, v3
	buffer_inv sc1
	v_sub_u32_e32 v3, 0, v2
	v_rcp_iflag_f32_e32 v4, v4
	v_add_u32_e32 v5, s0, v1
	v_mul_f32_e32 v4, 0x4f7ffffe, v4
	v_cvt_u32_f32_e32 v4, v4
	v_mul_lo_u32 v1, v3, v4
	v_mul_hi_u32 v1, v4, v1
	v_add_u32_e32 v1, v4, v1
	v_mul_hi_u32 v1, v5, v1
	v_mul_lo_u32 v3, v1, v2
	v_sub_u32_e32 v3, v5, v3
	v_add_u32_e32 v4, 1, v1
	v_cmp_ge_u32_e32 vcc, v3, v2
	s_nop 1
	v_cndmask_b32_e32 v1, v1, v4, vcc
	v_sub_u32_e32 v4, v3, v2
	v_cndmask_b32_e32 v3, v3, v4, vcc
	v_add_u32_e32 v4, 1, v1
	v_cmp_ge_u32_e32 vcc, v3, v2
	v_add_u32_e32 v3, 1, v5
	s_nop 0
	v_cndmask_b32_e32 v1, v1, v4, vcc
	v_mul_lo_u32 v4, v2, v1
	v_add_u32_e32 v2, v4, v2
	v_cmp_ne_u32_e32 vcc, v3, v2
	s_and_saveexec_b64 s[0:1], vcc
	s_xor_b64 s[8:9], exec, s[0:1]
	s_cbranch_execz .LBB0_1207
	s_waitcnt lgkmcnt(0)
	v_mov_b32_e32 v0, 0x2000
	global_load_dword v0, v0, s[6:7] offset:1024 sc1
	s_add_u32 s14, s6, 0x2400
	s_addc_u32 s15, s7, 0
	s_waitcnt vmcnt(0)
	v_cmp_eq_u32_e32 vcc, v0, v1
	s_and_saveexec_b64 s[10:11], vcc
	s_cbranch_execz .LBB0_1206
	s_add_u32 s12, s86, 0xe7c1200
	s_addc_u32 s13, s87, 0
	s_mov_b32 s0, 1
	s_mov_b64 s[16:17], 0
	v_mov_b32_e32 v0, 0
	s_branch .LBB0_1197

; DI unsigned xb_ld(unsigned* p) { return __hip_atomic_load(p, __ATOMIC_RELAXED, __HIP_MEMORY_SCOPE_AGENT); }
; DI unsigned xb_add(unsigned* p, unsigned v) { return __hip_atomic_fetch_add(p, v, __ATOMIC_RELAXED, __HIP_MEMORY_SCOPE_AGENT); }
; #define XB_SPIN(cond, bar) do { unsigned _sp = 0; while (cond) { __builtin_amdgcn_s_sleep(1); \
;     if ((++_sp & 255u) == 0u) { if (xb_ld(&(bar)[XB_TMO])) break; if (_sp > XB_SPIN_CAP) { atomicAdd(&(bar)[XB_TMO], 1u); break; } } } } while (0)
; DI void xcd_barrier(const XcdBarrier& b) {
;     ...
;     if (old + 1u == (gen + 1u) * nloc) {
;       __builtin_amdgcn_fence(__ATOMIC_RELEASE, "agent");
;       asm volatile("s_waitcnt vmcnt(0)" ::: "memory");
;       const unsigned og = xb_add(&bar[XB_TOP], 1u);
;       const unsigned tg = og / nx;
;       if (og + 1u == (tg + 1u) * nx) xb_add(&bar[XB_TOPGEN], 1u);
;       else XB_SPIN(xb_ld(&bar[XB_TOPGEN]) == tg, bar);
;       __builtin_amdgcn_fence(__ATOMIC_ACQUIRE, "agent");
;       xb_add(&bar[XB_XGEN(b.x)], 1u);
;       asm volatile("s_waitcnt vmcnt(0)" ::: "memory");
;     } else {
;       XB_SPIN(xb_ld(&bar[XB_XGEN(b.x)]) == gen, bar);
;       __builtin_amdgcn_fence(__ATOMIC_ACQUIRE, "agent");
;       asm volatile("s_waitcnt vmcnt(0)" ::: "memory");
.LBB0_1206:
	s_or_b64 exec, exec, s[10:11]
	s_waitcnt vmcnt(0)
	s_waitcnt vmcnt(0)
.LBB0_1207:
	s_andn2_saveexec_b64 s[0:1], s[8:9]
	s_cbranch_execz .LBB0_1227
	s_mov_b64 s[8:9], exec
	buffer_wbl2 sc1
	s_waitcnt lgkmcnt(0)
	s_waitcnt vmcnt(0)
	buffer_inv sc1
	v_mbcnt_lo_u32_b32 v1, s8, 0
	v_mbcnt_hi_u32_b32 v1, s9, v1
	v_cmp_eq_u32_e32 vcc, 0, v1
	s_and_saveexec_b64 s[10:11], vcc
	s_cbranch_execz .LBB0_1210
	s_bcnt1_i32_b64 s0, s[8:9]
	v_mov_b32_e32 v2, 0xe7c4000
	v_mov_b32_e32 v3, s0
	global_atomic_add v2, v2, v3, s[86:87] offset:1024 sc0

; DI unsigned xb_ld(unsigned* p) { return __hip_atomic_load(p, __ATOMIC_RELAXED, __HIP_MEMORY_SCOPE_AGENT); }
; DI unsigned xb_add(unsigned* p, unsigned v) { return __hip_atomic_fetch_add(p, v, __ATOMIC_RELAXED, __HIP_MEMORY_SCOPE_AGENT); }
; #define XB_SPIN(cond, bar) do { unsigned _sp = 0; while (cond) { __builtin_amdgcn_s_sleep(1); \
;     if ((++_sp & 255u) == 0u) { if (xb_ld(&(bar)[XB_TMO])) break; if (_sp > XB_SPIN_CAP) { atomicAdd(&(bar)[XB_TMO], 1u); break; } } } } while (0)
; DI void xcd_barrier(const XcdBarrier& b) {
;     ...
;       else XB_SPIN(xb_ld(&bar[XB_TOPGEN]) == tg, bar);
;       __builtin_amdgcn_fence(__ATOMIC_ACQUIRE, "agent");
;       xb_add(&bar[XB_XGEN(b.x)], 1u);
.LBB0_1224:
	s_or_b64 exec, exec, s[8:9]
	s_mov_b64 s[8:9], exec
	v_mbcnt_lo_u32_b32 v0, s8, 0
	v_mbcnt_hi_u32_b32 v0, s9, v0
	v_cmp_eq_u32_e32 vcc, 0, v0
	s_waitcnt vmcnt(0)
	s_and_saveexec_b64 s[10:11], vcc
	s_cbranch_execz .LBB0_1226
	s_bcnt1_i32_b64 s0, s[8:9]
	v_mov_b32_e32 v0, 0x2000
	v_mov_b32_e32 v1, s0
	global_atomic_add v0, v1, s[6:7] offset:1024

; DI unsigned xb_ld(unsigned* p) { return __hip_atomic_load(p, __ATOMIC_RELAXED, __HIP_MEMORY_SCOPE_AGENT); }
; DI unsigned xb_add(unsigned* p, unsigned v) { return __hip_atomic_fetch_add(p, v, __ATOMIC_RELAXED, __HIP_MEMORY_SCOPE_AGENT); }
; #define XB_SPIN(cond, bar) do { unsigned _sp = 0; while (cond) { __builtin_amdgcn_s_sleep(1); \
;     if ((++_sp & 255u) == 0u) { if (xb_ld(&(bar)[XB_TMO])) break; if (_sp > XB_SPIN_CAP) { atomicAdd(&(bar)[XB_TMO], 1u); break; } } } } while (0)
; DI void xcd_barrier(const XcdBarrier& b) {
;     ...
;     const unsigned old = xb_add(&bar[XB_XSUB(b.x)], 1u);
;     const unsigned gen = old / nloc;
;     if (old + 1u == (gen + 1u) * nloc) {
;       __builtin_amdgcn_fence(__ATOMIC_RELEASE, "agent");
;       asm volatile("s_waitcnt vmcnt(0)" ::: "memory");
;       const unsigned og = xb_add(&bar[XB_TOP], 1u);
;       const unsigned tg = og / nx;
;       if (og + 1u == (tg + 1u) * nx) xb_add(&bar[XB_TOPGEN], 1u);
;       else XB_SPIN(xb_ld(&bar[XB_TOPGEN]) == tg, bar);
;       __builtin_amdgcn_fence(__ATOMIC_ACQUIRE, "agent");
;       xb_add(&bar[XB_XGEN(b.x)], 1u);
;       asm volatile("s_waitcnt vmcnt(0)" ::: "memory");
;     } else {
;       XB_SPIN(xb_ld(&bar[XB_XGEN(b.x)]) == gen, bar);
.LBB0_1376:
	s_or_b64 exec, exec, s[12:13]
	v_cvt_f32_u32_e32 v4, v2
	s_waitcnt vmcnt(0)
	v_readfirstlane_b32 s2, v3
	buffer_inv sc1
	v_sub_u32_e32 v3, 0, v2
	v_rcp_iflag_f32_e32 v4, v4
	v_add_u32_e32 v5, s2, v1
	v_mul_f32_e32 v4, 0x4f7ffffe, v4
	v_cvt_u32_f32_e32 v4, v4
	v_mul_lo_u32 v1, v3, v4
	v_mul_hi_u32 v1, v4, v1
	v_add_u32_e32 v1, v4, v1
	v_mul_hi_u32 v1, v5, v1
	v_mul_lo_u32 v3, v1, v2
	v_sub_u32_e32 v3, v5, v3
	v_add_u32_e32 v4, 1, v1
	v_cmp_ge_u32_e32 vcc, v3, v2
	s_nop 1
	v_cndmask_b32_e32 v1, v1, v4, vcc
	v_sub_u32_e32 v4, v3, v2
	v_cndmask_b32_e32 v3, v3, v4, vcc
	v_add_u32_e32 v4, 1, v1
	v_cmp_ge_u32_e32 vcc, v3, v2
	v_add_u32_e32 v3, 1, v5
	s_nop 0
	v_cndmask_b32_e32 v1, v1, v4, vcc
	v_mul_lo_u32 v4, v2, v1
	v_add_u32_e32 v2, v4, v2
	v_cmp_ne_u32_e32 vcc, v3, v2
	s_and_saveexec_b64 s[8:9], vcc
	s_xor_b64 s[8:9], exec, s[8:9]
	s_cbranch_execz .LBB0_1390
	s_waitcnt lgkmcnt(0)
	v_mov_b32_e32 v0, 0x2000
	global_load_dword v0, v0, s[6:7] offset:1024 sc1
	s_add_u32 s16, s6, 0x2400
	s_addc_u32 s17, s7, 0
	s_waitcnt vmcnt(0)
	v_cmp_eq_u32_e32 vcc, v0, v1
	s_and_saveexec_b64 s[12:13], vcc
	s_cbranch_execz .LBB0_1389
	s_add_u32 s14, s86, 0xe7c1200
	s_addc_u32 s15, s87, 0
	s_mov_b32 s3, 1
	s_mov_b64 s[18:19], 0
	v_mov_b32_e32 v0, 0
	s_branch .LBB0_1380

; DI unsigned xb_add(unsigned* p, unsigned v) { return __hip_atomic_fetch_add(p, v, __ATOMIC_RELAXED, __HIP_MEMORY_SCOPE_AGENT); }
; DI void xcd_barrier(const XcdBarrier& b) {
;     ...
;     if (old + 1u == (gen + 1u) * nloc) {
;       __builtin_amdgcn_fence(__ATOMIC_RELEASE, "agent");
;       asm volatile("s_waitcnt vmcnt(0)" ::: "memory");
;       const unsigned og = xb_add(&bar[XB_TOP], 1u);
;       const unsigned tg = og / nx;
;       if (og + 1u == (tg + 1u) * nx) xb_add(&bar[XB_TOPGEN], 1u);
.LBB0_1390:
	s_andn2_saveexec_b64 s[8:9], s[8:9]
	s_cbranch_execz .LBB0_1410
	s_mov_b64 s[8:9], exec
	buffer_wbl2 sc1
	s_waitcnt lgkmcnt(0)
	s_waitcnt vmcnt(0)
	buffer_inv sc1
	v_mbcnt_lo_u32_b32 v1, s8, 0
	v_mbcnt_hi_u32_b32 v1, s9, v1
	v_cmp_eq_u32_e32 vcc, 0, v1
	s_and_saveexec_b64 s[12:13], vcc
	s_cbranch_execz .LBB0_1393
	s_bcnt1_i32_b64 s2, s[8:9]
	v_mov_b32_e32 v2, 0xe7c4000
	v_mov_b32_e32 v3, s2
	global_atomic_add v2, v2, v3, s[86:87] offset:1024 sc0

; DI unsigned xb_ld(unsigned* p) { return __hip_atomic_load(p, __ATOMIC_RELAXED, __HIP_MEMORY_SCOPE_AGENT); }
; DI unsigned xb_add(unsigned* p, unsigned v) { return __hip_atomic_fetch_add(p, v, __ATOMIC_RELAXED, __HIP_MEMORY_SCOPE_AGENT); }
; #define XB_SPIN(cond, bar) do { unsigned _sp = 0; while (cond) { __builtin_amdgcn_s_sleep(1); \
;     if ((++_sp & 255u) == 0u) { if (xb_ld(&(bar)[XB_TMO])) break; if (_sp > XB_SPIN_CAP) { atomicAdd(&(bar)[XB_TMO], 1u); break; } } } } while (0)
; DI void xcd_barrier(const XcdBarrier& b) {
;     ...
;       else XB_SPIN(xb_ld(&bar[XB_TOPGEN]) == tg, bar);
;       __builtin_amdgcn_fence(__ATOMIC_ACQUIRE, "agent");
;       xb_add(&bar[XB_XGEN(b.x)], 1u);
.LBB0_1407:
	s_or_b64 exec, exec, s[8:9]
	s_mov_b64 s[8:9], exec
	v_mbcnt_lo_u32_b32 v0, s8, 0
	v_mbcnt_hi_u32_b32 v0, s9, v0
	v_cmp_eq_u32_e32 vcc, 0, v0
	s_waitcnt vmcnt(0)
	s_and_saveexec_b64 s[12:13], vcc
	s_cbranch_execz .LBB0_1409
	s_bcnt1_i32_b64 s2, s[8:9]
	v_mov_b32_e32 v0, 0x2000
	v_mov_b32_e32 v1, s2
	global_atomic_add v0, v1, s[6:7] offset:1024

; DI unsigned xb_ld(unsigned* p) { return __hip_atomic_load(p, __ATOMIC_RELAXED, __HIP_MEMORY_SCOPE_AGENT); }
; DI unsigned xb_add(unsigned* p, unsigned v) { return __hip_atomic_fetch_add(p, v, __ATOMIC_RELAXED, __HIP_MEMORY_SCOPE_AGENT); }
; #define XB_SPIN(cond, bar) do { unsigned _sp = 0; while (cond) { __builtin_amdgcn_s_sleep(1); \
;     if ((++_sp & 255u) == 0u) { if (xb_ld(&(bar)[XB_TMO])) break; if (_sp > XB_SPIN_CAP) { atomicAdd(&(bar)[XB_TMO], 1u); break; } } } } while (0)
; DI void xcd_barrier(const XcdBarrier& b) {
;     ...
;     const unsigned old = xb_add(&bar[XB_XSUB(b.x)], 1u);
;     const unsigned gen = old / nloc;
;     if (old + 1u == (gen + 1u) * nloc) {
;       __builtin_amdgcn_fence(__ATOMIC_RELEASE, "agent");
;       asm volatile("s_waitcnt vmcnt(0)" ::: "memory");
;       const unsigned og = xb_add(&bar[XB_TOP], 1u);
;       const unsigned tg = og / nx;
;       if (og + 1u == (tg + 1u) * nx) xb_add(&bar[XB_TOPGEN], 1u);
;       else XB_SPIN(xb_ld(&bar[XB_TOPGEN]) == tg, bar);
;       __builtin_amdgcn_fence(__ATOMIC_ACQUIRE, "agent");
;       xb_add(&bar[XB_XGEN(b.x)], 1u);
;       asm volatile("s_waitcnt vmcnt(0)" ::: "memory");
;     } else {
;       XB_SPIN(xb_ld(&bar[XB_XGEN(b.x)]) == gen, bar);
.LBB0_1501:
	s_or_b64 exec, exec, s[6:7]
	v_cvt_f32_u32_e32 v4, v2
	s_waitcnt vmcnt(0)
	v_readfirstlane_b32 s4, v3
	buffer_inv sc1
	v_sub_u32_e32 v3, 0, v2
	v_rcp_iflag_f32_e32 v4, v4
	v_add_u32_e32 v5, s4, v1
	v_mul_f32_e32 v4, 0x4f7ffffe, v4
	v_cvt_u32_f32_e32 v4, v4
	v_mul_lo_u32 v1, v3, v4
	v_mul_hi_u32 v1, v4, v1
	v_add_u32_e32 v1, v4, v1
	v_mul_hi_u32 v1, v5, v1
	v_mul_lo_u32 v3, v1, v2
	v_sub_u32_e32 v3, v5, v3
	v_add_u32_e32 v4, 1, v1
	v_cmp_ge_u32_e32 vcc, v3, v2
	s_nop 1
	v_cndmask_b32_e32 v1, v1, v4, vcc
	v_sub_u32_e32 v4, v3, v2
	v_cndmask_b32_e32 v3, v3, v4, vcc
	v_add_u32_e32 v4, 1, v1
	v_cmp_ge_u32_e32 vcc, v3, v2
	v_add_u32_e32 v3, 1, v5
	s_nop 0
	v_cndmask_b32_e32 v1, v1, v4, vcc
	v_mul_lo_u32 v4, v2, v1
	v_add_u32_e32 v2, v4, v2
	v_cmp_ne_u32_e32 vcc, v3, v2
	s_and_saveexec_b64 s[4:5], vcc
	s_xor_b64 s[4:5], exec, s[4:5]
	s_cbranch_execz .LBB0_1515
	s_waitcnt lgkmcnt(0)
	v_mov_b32_e32 v0, 0x2000
	global_load_dword v0, v0, s[0:1] offset:1024 sc1
	s_add_u32 s10, s0, 0x2400
	s_addc_u32 s11, s1, 0
	s_waitcnt vmcnt(0)
	v_cmp_eq_u32_e32 vcc, v0, v1
	s_and_saveexec_b64 s[6:7], vcc
	s_cbranch_execz .LBB0_1514
	s_add_u32 s8, s86, 0xe7c1200
	s_addc_u32 s9, s87, 0
	s_mov_b32 s22, 1
	s_mov_b64 s[12:13], 0
	v_mov_b32_e32 v0, 0
	s_branch .LBB0_1505

; DI unsigned xb_ld(unsigned* p) { return __hip_atomic_load(p, __ATOMIC_RELAXED, __HIP_MEMORY_SCOPE_AGENT); }
; DI unsigned xb_add(unsigned* p, unsigned v) { return __hip_atomic_fetch_add(p, v, __ATOMIC_RELAXED, __HIP_MEMORY_SCOPE_AGENT); }
; #define XB_SPIN(cond, bar) do { unsigned _sp = 0; while (cond) { __builtin_amdgcn_s_sleep(1); \
;     if ((++_sp & 255u) == 0u) { if (xb_ld(&(bar)[XB_TMO])) break; if (_sp > XB_SPIN_CAP) { atomicAdd(&(bar)[XB_TMO], 1u); break; } } } } while (0)
; DI void xcd_barrier(const XcdBarrier& b) {
;     ...
;     if (old + 1u == (gen + 1u) * nloc) {
;       __builtin_amdgcn_fence(__ATOMIC_RELEASE, "agent");
;       asm volatile("s_waitcnt vmcnt(0)" ::: "memory");
;       const unsigned og = xb_add(&bar[XB_TOP], 1u);
;       const unsigned tg = og / nx;
;       if (og + 1u == (tg + 1u) * nx) xb_add(&bar[XB_TOPGEN], 1u);
;       else XB_SPIN(xb_ld(&bar[XB_TOPGEN]) == tg, bar);
;       __builtin_amdgcn_fence(__ATOMIC_ACQUIRE, "agent");
;       xb_add(&bar[XB_XGEN(b.x)], 1u);
;       asm volatile("s_waitcnt vmcnt(0)" ::: "memory");
;     } else {
;       XB_SPIN(xb_ld(&bar[XB_XGEN(b.x)]) == gen, bar);
;       __builtin_amdgcn_fence(__ATOMIC_ACQUIRE, "agent");
;       asm volatile("s_waitcnt vmcnt(0)" ::: "memory");
.LBB0_1514:
	s_or_b64 exec, exec, s[6:7]
	s_waitcnt vmcnt(0)
	s_waitcnt vmcnt(0)
.LBB0_1515:
	s_andn2_saveexec_b64 s[4:5], s[4:5]
	s_cbranch_execz .LBB0_1535
	s_mov_b64 s[4:5], exec
	buffer_wbl2 sc1
	s_waitcnt lgkmcnt(0)
	s_waitcnt vmcnt(0)
	buffer_inv sc1
	v_mbcnt_lo_u32_b32 v1, s4, 0
	v_mbcnt_hi_u32_b32 v1, s5, v1
	v_cmp_eq_u32_e32 vcc, 0, v1
	s_and_saveexec_b64 s[6:7], vcc
	s_cbranch_execz .LBB0_1518
	s_bcnt1_i32_b64 s4, s[4:5]
	v_mov_b32_e32 v2, 0xe7c4000
	v_mov_b32_e32 v3, s4
	global_atomic_add v2, v2, v3, s[86:87] offset:1024 sc0

; DI unsigned xb_ld(unsigned* p) { return __hip_atomic_load(p, __ATOMIC_RELAXED, __HIP_MEMORY_SCOPE_AGENT); }
; DI unsigned xb_add(unsigned* p, unsigned v) { return __hip_atomic_fetch_add(p, v, __ATOMIC_RELAXED, __HIP_MEMORY_SCOPE_AGENT); }
; #define XB_SPIN(cond, bar) do { unsigned _sp = 0; while (cond) { __builtin_amdgcn_s_sleep(1); \
;     if ((++_sp & 255u) == 0u) { if (xb_ld(&(bar)[XB_TMO])) break; if (_sp > XB_SPIN_CAP) { atomicAdd(&(bar)[XB_TMO], 1u); break; } } } } while (0)
; DI void xcd_barrier(const XcdBarrier& b) {
;     ...
;       else XB_SPIN(xb_ld(&bar[XB_TOPGEN]) == tg, bar);
;       __builtin_amdgcn_fence(__ATOMIC_ACQUIRE, "agent");
;       xb_add(&bar[XB_XGEN(b.x)], 1u);
.LBB0_1532:
	s_or_b64 exec, exec, s[4:5]
	s_mov_b64 s[4:5], exec
	v_mbcnt_lo_u32_b32 v0, s4, 0
	v_mbcnt_hi_u32_b32 v0, s5, v0
	v_cmp_eq_u32_e32 vcc, 0, v0
	s_waitcnt vmcnt(0)
	s_and_saveexec_b64 s[6:7], vcc
	s_cbranch_execz .LBB0_1534
	s_bcnt1_i32_b64 s4, s[4:5]
	v_mov_b32_e32 v0, 0x2000
	v_mov_b32_e32 v1, s4
	global_atomic_add v0, v1, s[0:1] offset:1024
